# residual-GEMM epilogues: the 8 fp16 residual-row loads of each thread hoisted to the start of the epilogue (one wait instead of 8 serialized load-modify-store round trips)
# speedup vs baseline: 1.0122x; 1.0075x over previous
; DI float hlo(unsigned u) { return h2f((bf16_t)(u & 0xffffu)); }
; DI float hhi(unsigned u) { return h2f((bf16_t)(u >> 16)); }
; DI int crow(int r, int h) { return (r & 3) + 8 * (r >> 2) + 4 * h; }
; DI void ph_res(KP p, const bf16_t* A, int K, const bf16_t* Wt, const float* xin, char* smem, bool dry) {
;     ...
; #pragma unroll
;         for (int i = 0; i < 2; ++i)
; #pragma unroll
;             for (int j = 0; j < 2; ++j)
; #pragma unroll
;                 for (int r = 0; r < 16; ++r) stg[(wm * 64 + i * 32 + crow(r, h)) * 132 + wn * 64 + j * 32 + l32] = acc[i][j][r];
;         __syncthreads();
;         bf16_t* xb = (bf16_t*)(p->ws + OFF_XB) + (size_t)(rt * 128) * DM + ct * 128;
;         float* part = (float*)(p->ws + OFF_RSC) + (size_t)(rt * 128) * 16 + ct * 2;
;         const int c8 = tt & 15;
; #pragma unroll
;         for (int i = 0; i < 8; ++i) {
;             const int row = (tt >> 4) + 16 * i;
;             const float4 lo = *(const float4*)(stg + row * 132 + c8 * 8), hi = *(const float4*)(stg + row * 132 + c8 * 8 + 4);
;             uint4* gp = (uint4*)(xb + (size_t)row * DM + c8 * 8);
;             const uint4 xv = *gp;
;             uint4 nv;
;             nv.x = pack2h(hlo(xv.x) + lo.x, hhi(xv.x) + lo.y); nv.y = pack2h(hlo(xv.y) + lo.z, hhi(xv.y) + lo.w);
;             nv.z = pack2h(hlo(xv.z) + hi.x, hhi(xv.z) + hi.y); nv.w = pack2h(hlo(xv.w) + hi.z, hhi(xv.w) + hi.w);
;             *gp = nv;
;             float s0 = hlo(nv.x), s1 = hhi(nv.x), s2 = hlo(nv.y), s3 = hhi(nv.y), s4 = hlo(nv.z), s5 = hhi(nv.z), s6 = hlo(nv.w), s7 = hhi(nv.w);
;             float sq = s0 * s0 + s1 * s1 + s2 * s2 + s3 * s3 + s4 * s4 + s5 * s5 + s6 * s6 + s7 * s7;
;             sq += __shfl_xor(sq, 1); sq += __shfl_xor(sq, 2); sq += __shfl_xor(sq, 4); sq += __shfl_xor(sq, 8);
;             if (c8 == 0) { float2 pv; pv.x = sq; pv.y = 0.f; *(float2*)(part + (size_t)row * 16) = pv; }
.LBB0_37:
	v_mov_b32_e32 v32, v182
	s_ashr_i32 s37, s36, 31
	v_readfirstlane_b32 s13, v32
	s_lshr_b32 s34, s13, 1
	v_and_b32_e32 v33, 31, v32
	s_and_b32 s34, s34, 0xfffffc0
	v_lshrrev_b32_e32 v34, 3, v32
	v_and_or_b32 v34, v34, 4, s34
	v_and_or_b32 v33, s13, 64, v33
	v_mul_lo_u32 v34, v34, s82
	v_lshlrev_b32_e32 v33, 2, v33
	v_add3_u32 v33, 0, v34, v33
	v_add_u32_e32 v34, 0x400, v33
	ds_write2_b32 v33, v52, v36 offset1:32
	ds_write2_b32 v33, v53, v37 offset0:132 offset1:164
	ds_write2_b32 v34, v54, v38 offset0:8 offset1:40
	ds_write2_b32 v34, v55, v39 offset0:140 offset1:172
	v_add_u32_e32 v34, 0x1000, v33
	ds_write2_b32 v34, v56, v40 offset0:32 offset1:64
	ds_write2_b32 v34, v57, v41 offset0:164 offset1:196
	v_add_u32_e32 v34, 0x1400, v33
	ds_write2_b32 v34, v58, v42 offset0:40 offset1:72
	ds_write2_b32 v34, v59, v43 offset0:172 offset1:204
	v_add_u32_e32 v34, 0x2000, v33
	ds_write2_b32 v34, v60, v44 offset0:64 offset1:96
	ds_write2_b32 v34, v61, v45 offset0:196 offset1:228
	v_add_u32_e32 v34, 0x2400, v33
	ds_write2_b32 v34, v62, v46 offset0:72 offset1:104
	ds_write2_b32 v34, v63, v47 offset0:204 offset1:236
	v_add_u32_e32 v34, 0x3000, v33
	ds_write2_b32 v34, v64, v48 offset0:96 offset1:128
	v_add_u32_e32 v34, 0x3200, v33
	ds_write2_b32 v34, v65, v49 offset0:100 offset1:132
	v_add_u32_e32 v34, 0x3400, v33
	ds_write2_b32 v34, v66, v50 offset0:104 offset1:136
	v_add_u32_e32 v34, 0x3600, v33
	ds_write2_b32 v34, v67, v51 offset0:108 offset1:140
	v_add_u32_e32 v34, 0x4000, v33
	ds_write2_b32 v34, v16, v0 offset0:128 offset1:160
	v_add_u32_e32 v0, 0x4400, v33
	ds_write2_b32 v0, v17, v1 offset0:4 offset1:36
	ds_write2_b32 v0, v18, v2 offset0:136 offset1:168
	v_add_u32_e32 v0, 0x4800, v33
	ds_write2_b32 v0, v19, v3 offset0:12 offset1:44
	v_add_u32_e32 v0, 0x5000, v33
	ds_write2_b32 v0, v20, v4 offset0:160 offset1:192
	v_add_u32_e32 v0, 0x5400, v33
	ds_write2_b32 v0, v21, v5 offset0:36 offset1:68
	ds_write2_b32 v0, v22, v6 offset0:168 offset1:200
	v_add_u32_e32 v0, 0x5800, v33
	ds_write2_b32 v0, v23, v7 offset0:44 offset1:76
	v_add_u32_e32 v0, 0x6000, v33
	s_lshl_b64 s[34:35], s[36:37], 11
	ds_write2_b32 v0, v24, v8 offset0:192 offset1:224
	v_add_u32_e32 v0, 0x6400, v33
	s_add_u32 s13, s7, s34
	ds_write2_b32 v0, v25, v9 offset0:68 offset1:100
	ds_write2_b32 v0, v26, v10 offset0:200 offset1:232
	v_add_u32_e32 v0, 0x6800, v33
	s_addc_u32 s42, s8, s35
	s_lshl_b32 s34, s12, 7
	ds_write2_b32 v0, v27, v11 offset0:76 offset1:108
	v_add_u32_e32 v0, 0x7200, v33
	s_ashr_i32 s35, s34, 31
	ds_write2_b32 v0, v28, v12 offset0:96 offset1:128
	v_add_u32_e32 v0, 0x7400, v33
	s_lshl_b64 s[34:35], s[34:35], 1
	ds_write2_b32 v0, v29, v13 offset0:100 offset1:132
	v_add_u32_e32 v0, 0x7600, v33
	s_add_u32 s34, s13, s34
	v_and_b32_e32 v11, 15, v32
	v_ashrrev_i32_e32 v2, 4, v32
	ds_write2_b32 v0, v30, v14 offset0:104 offset1:136
	v_add_u32_e32 v0, 0x7800, v33
	s_addc_u32 s35, s42, s35
	v_lshlrev_b32_e32 v34, 4, v11
	v_ashrrev_i32_e32 v3, 31, v2
	ds_write2_b32 v0, v31, v15 offset0:108 offset1:140
	v_lshl_add_u64 v[0:1], s[34:35], 0, v[34:35]
	v_lshlrev_b64 v[4:5], 11, v[2:3]
	v_lshl_add_u64 v[24:25], v[0:1], 0, v[4:5]
	s_waitcnt lgkmcnt(0)
	s_barrier
	global_load_dwordx4 v[12:15], v[24:25], off
	v_add_co_u32_e32 v26, vcc, 0x8000, v24
	s_nop 1
	v_addc_co_u32_e32 v27, vcc, 0, v25, vcc
	global_load_dwordx4 v[40:43], v[26:27], off
	v_add_co_u32_e32 v26, vcc, 0x8000, v26
	s_nop 1
	v_addc_co_u32_e32 v27, vcc, 0, v27, vcc
	global_load_dwordx4 v[44:47], v[26:27], off
	v_add_co_u32_e32 v26, vcc, 0x8000, v26
	s_nop 1
	v_addc_co_u32_e32 v27, vcc, 0, v27, vcc
	global_load_dwordx4 v[48:51], v[26:27], off
	v_add_co_u32_e32 v26, vcc, 0x8000, v26
	s_nop 1
	v_addc_co_u32_e32 v27, vcc, 0, v27, vcc
	global_load_dwordx4 v[52:55], v[26:27], off
	v_add_co_u32_e32 v26, vcc, 0x8000, v26
	s_nop 1
	v_addc_co_u32_e32 v27, vcc, 0, v27, vcc
	global_load_dwordx4 v[56:59], v[26:27], off
	v_add_co_u32_e32 v26, vcc, 0x8000, v26
	s_nop 1
	v_addc_co_u32_e32 v27, vcc, 0, v27, vcc
	global_load_dwordx4 v[60:63], v[26:27], off
	v_add_co_u32_e32 v26, vcc, 0x8000, v26
	s_nop 1
	v_addc_co_u32_e32 v27, vcc, 0, v27, vcc
	global_load_dwordx4 v[64:67], v[26:27], off
	v_cmp_lt_i32_e32 vcc, v186, v187
	v_lshl_add_u32 v4, v11, 5, 0
	s_lshl_b64 s[34:35], s[36:37], 6
	v_cndmask_b32_e32 v5, v184, v186, vcc
	v_lshlrev_b32_e32 v6, 2, v5
	v_mul_lo_u32 v5, v2, s82
	v_add_u32_e32 v10, v4, v5
	ds_read_b128 v[16:19], v10
	ds_read_b128 v[20:23], v10 offset:16
	v_cmp_lt_i32_e32 vcc, v188, v187
	s_add_u32 s34, s9, s34
	s_addc_u32 s35, s10, s35
	s_lshl_b32 s12, s12, 1
	s_ashr_i32 s13, s12, 31
	s_lshl_b64 s[12:13], s[12:13], 2
	s_add_u32 s36, s34, s12
	s_addc_u32 s37, s35, s13
	s_waitcnt vmcnt(0)
	v_cvt_f32_f16_e32 v4, v12
	v_cvt_f32_f16_sdwa v5, v12 dst_sel:DWORD dst_unused:UNUSED_PAD src0_sel:WORD_1
	v_cvt_f32_f16_e32 v8, v13
	v_cvt_f32_f16_sdwa v9, v13 dst_sel:DWORD dst_unused:UNUSED_PAD src0_sel:WORD_1
	s_waitcnt lgkmcnt(1)
	v_pk_add_f32 v[4:5], v[16:17], v[4:5]
	s_nop 0
	v_cvt_pk_f16_f32 v12, v4, v5
	v_pk_add_f32 v[4:5], v[18:19], v[8:9]
	v_cvt_f32_f16_sdwa v7, v12 dst_sel:DWORD dst_unused:UNUSED_PAD src0_sel:WORD_1
	v_cvt_pk_f16_f32 v13, v4, v5
	v_cvt_f32_f16_e32 v4, v15
	v_cvt_f32_f16_sdwa v5, v15 dst_sel:DWORD dst_unused:UNUSED_PAD src0_sel:WORD_1
	v_cvt_f32_f16_e32 v8, v14
	v_cvt_f32_f16_sdwa v9, v14 dst_sel:DWORD dst_unused:UNUSED_PAD src0_sel:WORD_1
	s_waitcnt lgkmcnt(0)
	v_pk_add_f32 v[4:5], v[22:23], v[4:5]
	s_nop 0
	v_cvt_pk_f16_f32 v15, v4, v5
	v_mul_f32_e32 v4, v7, v7
	v_fma_mix_f32 v4, v12, v12, v4 op_sel_hi:[1,1,0]
	v_pk_add_f32 v[8:9], v[20:21], v[8:9]
	v_fma_mix_f32 v4, v13, v13, v4 op_sel_hi:[1,1,0]
	v_cvt_pk_f16_f32 v14, v8, v9
	v_fma_mix_f32 v4, v13, v13, v4 op_sel:[1,1,0] op_sel_hi:[1,1,0]
	v_cndmask_b32_e32 v7, v184, v188, vcc
	v_fma_mix_f32 v4, v14, v14, v4 op_sel_hi:[1,1,0]
	v_lshlrev_b32_e32 v7, 2, v7
	v_fma_mix_f32 v4, v14, v14, v4 op_sel:[1,1,0] op_sel_hi:[1,1,0]
	v_cmp_lt_i32_e32 vcc, v189, v187
	v_fma_mix_f32 v4, v15, v15, v4 op_sel_hi:[1,1,0]
	global_store_dwordx4 v[24:25], v[12:15], off
	v_fma_mix_f32 v4, v15, v15, v4 op_sel:[1,1,0] op_sel_hi:[1,1,0]
	s_nop 1
	v_add_f32_dpp v4, v4, v4 quad_perm:[1,0,3,2] row_mask:0xf bank_mask:0xf
	v_cndmask_b32_e32 v8, v184, v189, vcc
	v_lshlrev_b32_e32 v8, 2, v8
	v_cmp_lt_i32_e32 vcc, v190, v187
	s_waitcnt lgkmcnt(0)
	s_nop 1
	v_add_f32_dpp v4, v4, v4 quad_perm:[2,3,0,1] row_mask:0xf bank_mask:0xf
	v_cndmask_b32_e32 v9, v184, v190, vcc
	v_lshlrev_b32_e32 v9, 2, v9
	v_cmp_eq_u32_e32 vcc, 0, v11
	s_waitcnt lgkmcnt(0)
	s_nop 1
	v_add_f32_dpp v4, v4, v4 row_half_mirror row_mask:0xf bank_mask:0xf
	s_waitcnt lgkmcnt(0)
	s_nop 1
	v_mov_b32_dpp v5, v4 row_mirror row_mask:0xf bank_mask:0xf
	s_and_saveexec_b64 s[42:43], vcc
	s_cbranch_execz .LBB0_39
	s_waitcnt lgkmcnt(0)
	v_add_f32_e32 v34, v4, v5
	v_lshlrev_b64 v[4:5], 6, v[2:3]
	v_lshl_add_u64 v[4:5], s[36:37], 0, v[4:5]
	global_store_dwordx2 v[4:5], v[34:35], off
; DI float hlo(unsigned u) { return h2f((bf16_t)(u & 0xffffu)); }
; DI float hhi(unsigned u) { return h2f((bf16_t)(u >> 16)); }
; DI void ph_res(KP p, const bf16_t* A, int K, const bf16_t* Wt, const float* xin, char* smem, bool dry) {
;     ...
;         for (int i = 0; i < 8; ++i) {
;             const int row = (tt >> 4) + 16 * i;
;             const float4 lo = *(const float4*)(stg + row * 132 + c8 * 8), hi = *(const float4*)(stg + row * 132 + c8 * 8 + 4);
;             uint4* gp = (uint4*)(xb + (size_t)row * DM + c8 * 8);
;             const uint4 xv = *gp;
;             uint4 nv;
;             nv.x = pack2h(hlo(xv.x) + lo.x, hhi(xv.x) + lo.y); nv.y = pack2h(hlo(xv.y) + lo.z, hhi(xv.y) + lo.w);
;             nv.z = pack2h(hlo(xv.z) + hi.x, hhi(xv.z) + hi.y); nv.w = pack2h(hlo(xv.w) + hi.z, hhi(xv.w) + hi.w);
;             *gp = nv;
;             float s0 = hlo(nv.x), s1 = hhi(nv.x), s2 = hlo(nv.y), s3 = hhi(nv.y), s4 = hlo(nv.z), s5 = hhi(nv.z), s6 = hlo(nv.w), s7 = hhi(nv.w);
;             float sq = s0 * s0 + s1 * s1 + s2 * s2 + s3 * s3 + s4 * s4 + s5 * s5 + s6 * s6 + s7 * s7;
;             sq += __shfl_xor(sq, 1); sq += __shfl_xor(sq, 2); sq += __shfl_xor(sq, 4); sq += __shfl_xor(sq, 8);
;             if (c8 == 0) { float2 pv; pv.x = sq; pv.y = 0.f; *(float2*)(part + (size_t)row * 16) = pv; }
.LBB0_39:
	s_or_b64 exec, exec, s[42:43]
	v_add_u32_e32 v4, 16, v2
	s_waitcnt lgkmcnt(0)
	v_ashrrev_i32_e32 v5, 31, v4
	v_lshlrev_b64 v[12:13], 11, v[4:5]
	v_lshl_add_u64 v[24:25], v[0:1], 0, v[12:13]
	v_mov_b64_e32 v[12:13], v[40:41]
	v_mov_b64_e32 v[14:15], v[42:43]
	ds_read_b128 v[16:19], v10 offset:8448
	ds_read_b128 v[20:23], v10 offset:8464
	v_cvt_f32_f16_e32 v26, v12
	v_cvt_f32_f16_sdwa v27, v12 dst_sel:DWORD dst_unused:UNUSED_PAD src0_sel:WORD_1
	s_waitcnt lgkmcnt(1)
	v_pk_add_f32 v[16:17], v[16:17], v[26:27]
	s_nop 0
	v_cvt_pk_f16_f32 v12, v16, v17
	v_cvt_f32_f16_e32 v16, v13
	v_cvt_f32_f16_sdwa v17, v13 dst_sel:DWORD dst_unused:UNUSED_PAD src0_sel:WORD_1
	v_cvt_f32_f16_sdwa v3, v12 dst_sel:DWORD dst_unused:UNUSED_PAD src0_sel:WORD_1
	v_pk_add_f32 v[16:17], v[18:19], v[16:17]
	s_nop 0
	v_cvt_pk_f16_f32 v13, v16, v17
	v_cvt_f32_f16_e32 v16, v14
	v_cvt_f32_f16_sdwa v17, v14 dst_sel:DWORD dst_unused:UNUSED_PAD src0_sel:WORD_1
	v_mul_f32_e32 v3, v3, v3
	v_fma_mix_f32 v3, v12, v12, v3 op_sel_hi:[1,1,0]
	s_waitcnt lgkmcnt(0)
	v_pk_add_f32 v[16:17], v[20:21], v[16:17]
	s_nop 0
	v_cvt_pk_f16_f32 v14, v16, v17
	v_cvt_f32_f16_e32 v16, v15
	v_cvt_f32_f16_sdwa v17, v15 dst_sel:DWORD dst_unused:UNUSED_PAD src0_sel:WORD_1
	v_fma_mix_f32 v3, v13, v13, v3 op_sel_hi:[1,1,0]
	v_pk_add_f32 v[16:17], v[22:23], v[16:17]
	v_fma_mix_f32 v3, v13, v13, v3 op_sel:[1,1,0] op_sel_hi:[1,1,0]
	v_cvt_pk_f16_f32 v15, v16, v17
	v_fma_mix_f32 v3, v14, v14, v3 op_sel_hi:[1,1,0]
	global_store_dwordx4 v[24:25], v[12:15], off
	v_fma_mix_f32 v3, v14, v14, v3 op_sel:[1,1,0] op_sel_hi:[1,1,0]
	s_nop 0
	v_fma_mix_f32 v3, v15, v15, v3 op_sel_hi:[1,1,0]
	s_nop 0
	v_fma_mix_f32 v3, v15, v15, v3 op_sel:[1,1,0] op_sel_hi:[1,1,0]
	s_nop 1
	v_add_f32_dpp v3, v3, v3 quad_perm:[1,0,3,2] row_mask:0xf bank_mask:0xf
	s_waitcnt lgkmcnt(0)
	s_nop 1
	v_add_f32_dpp v3, v3, v3 quad_perm:[2,3,0,1] row_mask:0xf bank_mask:0xf
	s_waitcnt lgkmcnt(0)
	s_nop 1
	v_add_f32_dpp v3, v3, v3 row_half_mirror row_mask:0xf bank_mask:0xf
	s_waitcnt lgkmcnt(0)
	s_nop 1
	v_mov_b32_dpp v11, v3 row_mirror row_mask:0xf bank_mask:0xf
	s_and_saveexec_b64 s[42:43], vcc
	s_cbranch_execz .LBB0_41
	v_lshlrev_b64 v[4:5], 6, v[4:5]
	s_waitcnt lgkmcnt(0)
	v_add_f32_e32 v34, v3, v11
	v_lshl_add_u64 v[4:5], s[36:37], 0, v[4:5]
	global_store_dwordx2 v[4:5], v[34:35], off
.LBB0_41:
	s_or_b64 exec, exec, s[42:43]
	v_add_u32_e32 v4, 32, v2
	v_ashrrev_i32_e32 v5, 31, v4
	v_lshlrev_b64 v[12:13], 11, v[4:5]
	v_lshl_add_u64 v[24:25], v[0:1], 0, v[12:13]
	v_mov_b64_e32 v[12:13], v[44:45]
	v_mov_b64_e32 v[14:15], v[46:47]
	ds_read_b128 v[16:19], v10 offset:16896
	ds_read_b128 v[20:23], v10 offset:16912
	v_cvt_f32_f16_e32 v26, v12
	v_cvt_f32_f16_sdwa v27, v12 dst_sel:DWORD dst_unused:UNUSED_PAD src0_sel:WORD_1
	s_waitcnt lgkmcnt(1)
	v_pk_add_f32 v[16:17], v[16:17], v[26:27]
	s_nop 0
	v_cvt_pk_f16_f32 v12, v16, v17
	v_cvt_f32_f16_e32 v16, v13
	v_cvt_f32_f16_sdwa v17, v13 dst_sel:DWORD dst_unused:UNUSED_PAD src0_sel:WORD_1
	v_cvt_f32_f16_sdwa v3, v12 dst_sel:DWORD dst_unused:UNUSED_PAD src0_sel:WORD_1
	v_pk_add_f32 v[16:17], v[18:19], v[16:17]
	s_nop 0
	v_cvt_pk_f16_f32 v13, v16, v17
	v_cvt_f32_f16_e32 v16, v14
	v_cvt_f32_f16_sdwa v17, v14 dst_sel:DWORD dst_unused:UNUSED_PAD src0_sel:WORD_1
	v_mul_f32_e32 v3, v3, v3
	v_fma_mix_f32 v3, v12, v12, v3 op_sel_hi:[1,1,0]
	s_waitcnt lgkmcnt(0)
	v_pk_add_f32 v[16:17], v[20:21], v[16:17]
	s_nop 0
	v_cvt_pk_f16_f32 v14, v16, v17
	v_cvt_f32_f16_e32 v16, v15
	v_cvt_f32_f16_sdwa v17, v15 dst_sel:DWORD dst_unused:UNUSED_PAD src0_sel:WORD_1
	v_fma_mix_f32 v3, v13, v13, v3 op_sel_hi:[1,1,0]
	v_pk_add_f32 v[16:17], v[22:23], v[16:17]
	v_fma_mix_f32 v3, v13, v13, v3 op_sel:[1,1,0] op_sel_hi:[1,1,0]
	v_cvt_pk_f16_f32 v15, v16, v17
	v_fma_mix_f32 v3, v14, v14, v3 op_sel_hi:[1,1,0]
	global_store_dwordx4 v[24:25], v[12:15], off
	v_fma_mix_f32 v3, v14, v14, v3 op_sel:[1,1,0] op_sel_hi:[1,1,0]
	s_nop 0
	v_fma_mix_f32 v3, v15, v15, v3 op_sel_hi:[1,1,0]
	s_nop 0
	v_fma_mix_f32 v3, v15, v15, v3 op_sel:[1,1,0] op_sel_hi:[1,1,0]
	s_nop 1
	v_add_f32_dpp v3, v3, v3 quad_perm:[1,0,3,2] row_mask:0xf bank_mask:0xf
	s_waitcnt lgkmcnt(0)
	s_nop 1
	v_add_f32_dpp v3, v3, v3 quad_perm:[2,3,0,1] row_mask:0xf bank_mask:0xf
	s_waitcnt lgkmcnt(0)
	s_nop 1
	v_add_f32_dpp v3, v3, v3 row_half_mirror row_mask:0xf bank_mask:0xf
	s_waitcnt lgkmcnt(0)
	s_nop 1
	v_mov_b32_dpp v11, v3 row_mirror row_mask:0xf bank_mask:0xf
	s_and_saveexec_b64 s[42:43], vcc
	s_cbranch_execz .LBB0_43
	v_lshlrev_b64 v[4:5], 6, v[4:5]
	s_waitcnt lgkmcnt(0)
	v_add_f32_e32 v34, v3, v11
	v_lshl_add_u64 v[4:5], s[36:37], 0, v[4:5]
	global_store_dwordx2 v[4:5], v[34:35], off
; DI float hlo(unsigned u) { return h2f((bf16_t)(u & 0xffffu)); }
; DI float hhi(unsigned u) { return h2f((bf16_t)(u >> 16)); }
; DI void ph_res(KP p, const bf16_t* A, int K, const bf16_t* Wt, const float* xin, char* smem, bool dry) {
;     ...
;         for (int i = 0; i < 8; ++i) {
;             const int row = (tt >> 4) + 16 * i;
;             const float4 lo = *(const float4*)(stg + row * 132 + c8 * 8), hi = *(const float4*)(stg + row * 132 + c8 * 8 + 4);
;             uint4* gp = (uint4*)(xb + (size_t)row * DM + c8 * 8);
;             const uint4 xv = *gp;
;             uint4 nv;
;             nv.x = pack2h(hlo(xv.x) + lo.x, hhi(xv.x) + lo.y); nv.y = pack2h(hlo(xv.y) + lo.z, hhi(xv.y) + lo.w);
;             nv.z = pack2h(hlo(xv.z) + hi.x, hhi(xv.z) + hi.y); nv.w = pack2h(hlo(xv.w) + hi.z, hhi(xv.w) + hi.w);
;             *gp = nv;
;             float s0 = hlo(nv.x), s1 = hhi(nv.x), s2 = hlo(nv.y), s3 = hhi(nv.y), s4 = hlo(nv.z), s5 = hhi(nv.z), s6 = hlo(nv.w), s7 = hhi(nv.w);
;             float sq = s0 * s0 + s1 * s1 + s2 * s2 + s3 * s3 + s4 * s4 + s5 * s5 + s6 * s6 + s7 * s7;
;             sq += __shfl_xor(sq, 1); sq += __shfl_xor(sq, 2); sq += __shfl_xor(sq, 4); sq += __shfl_xor(sq, 8);
;             if (c8 == 0) { float2 pv; pv.x = sq; pv.y = 0.f; *(float2*)(part + (size_t)row * 16) = pv; }
.LBB0_43:
	s_or_b64 exec, exec, s[42:43]
	v_add_u32_e32 v4, 48, v2
	v_ashrrev_i32_e32 v5, 31, v4
	v_lshlrev_b64 v[12:13], 11, v[4:5]
	v_lshl_add_u64 v[24:25], v[0:1], 0, v[12:13]
	v_mov_b64_e32 v[12:13], v[48:49]
	v_mov_b64_e32 v[14:15], v[50:51]
	ds_read_b128 v[16:19], v10 offset:25344
	ds_read_b128 v[20:23], v10 offset:25360
	v_cvt_f32_f16_e32 v26, v12
	v_cvt_f32_f16_sdwa v27, v12 dst_sel:DWORD dst_unused:UNUSED_PAD src0_sel:WORD_1
	s_waitcnt lgkmcnt(1)
	v_pk_add_f32 v[16:17], v[16:17], v[26:27]
	s_nop 0
	v_cvt_pk_f16_f32 v12, v16, v17
	v_cvt_f32_f16_e32 v16, v13
	v_cvt_f32_f16_sdwa v17, v13 dst_sel:DWORD dst_unused:UNUSED_PAD src0_sel:WORD_1
	v_cvt_f32_f16_sdwa v3, v12 dst_sel:DWORD dst_unused:UNUSED_PAD src0_sel:WORD_1
	v_pk_add_f32 v[16:17], v[18:19], v[16:17]
	s_nop 0
	v_cvt_pk_f16_f32 v13, v16, v17
	v_cvt_f32_f16_e32 v16, v14
	v_cvt_f32_f16_sdwa v17, v14 dst_sel:DWORD dst_unused:UNUSED_PAD src0_sel:WORD_1
	v_mul_f32_e32 v3, v3, v3
	v_fma_mix_f32 v3, v12, v12, v3 op_sel_hi:[1,1,0]
	s_waitcnt lgkmcnt(0)
	v_pk_add_f32 v[16:17], v[20:21], v[16:17]
	s_nop 0
	v_cvt_pk_f16_f32 v14, v16, v17
	v_cvt_f32_f16_e32 v16, v15
	v_cvt_f32_f16_sdwa v17, v15 dst_sel:DWORD dst_unused:UNUSED_PAD src0_sel:WORD_1
	v_fma_mix_f32 v3, v13, v13, v3 op_sel_hi:[1,1,0]
	v_pk_add_f32 v[16:17], v[22:23], v[16:17]
	v_fma_mix_f32 v3, v13, v13, v3 op_sel:[1,1,0] op_sel_hi:[1,1,0]
	v_cvt_pk_f16_f32 v15, v16, v17
	v_fma_mix_f32 v3, v14, v14, v3 op_sel_hi:[1,1,0]
	global_store_dwordx4 v[24:25], v[12:15], off
	v_fma_mix_f32 v3, v14, v14, v3 op_sel:[1,1,0] op_sel_hi:[1,1,0]
	s_nop 0
	v_fma_mix_f32 v3, v15, v15, v3 op_sel_hi:[1,1,0]
	s_nop 0
	v_fma_mix_f32 v3, v15, v15, v3 op_sel:[1,1,0] op_sel_hi:[1,1,0]
	s_nop 1
	v_add_f32_dpp v3, v3, v3 quad_perm:[1,0,3,2] row_mask:0xf bank_mask:0xf
	s_waitcnt lgkmcnt(0)
	s_nop 1
	v_add_f32_dpp v3, v3, v3 quad_perm:[2,3,0,1] row_mask:0xf bank_mask:0xf
	s_waitcnt lgkmcnt(0)
	s_nop 1
	v_add_f32_dpp v3, v3, v3 row_half_mirror row_mask:0xf bank_mask:0xf
	s_waitcnt lgkmcnt(0)
	s_nop 1
	v_mov_b32_dpp v11, v3 row_mirror row_mask:0xf bank_mask:0xf
	s_and_saveexec_b64 s[42:43], vcc
	s_cbranch_execz .LBB0_45
	v_lshlrev_b64 v[4:5], 6, v[4:5]
	s_waitcnt lgkmcnt(0)
	v_add_f32_e32 v34, v3, v11
	v_lshl_add_u64 v[4:5], s[36:37], 0, v[4:5]
	global_store_dwordx2 v[4:5], v[34:35], off
.LBB0_45:
	s_or_b64 exec, exec, s[42:43]
	v_add_u32_e32 v4, 64, v2
	v_ashrrev_i32_e32 v5, 31, v4
	v_lshlrev_b64 v[12:13], 11, v[4:5]
	v_lshl_add_u64 v[24:25], v[0:1], 0, v[12:13]
	v_mov_b64_e32 v[12:13], v[52:53]
	v_mov_b64_e32 v[14:15], v[54:55]
	ds_read_b128 v[16:19], v10 offset:33792
	ds_read_b128 v[20:23], v10 offset:33808
	v_cvt_f32_f16_e32 v26, v12
	v_cvt_f32_f16_sdwa v27, v12 dst_sel:DWORD dst_unused:UNUSED_PAD src0_sel:WORD_1
	s_waitcnt lgkmcnt(1)
	v_pk_add_f32 v[16:17], v[16:17], v[26:27]
	s_nop 0
	v_cvt_pk_f16_f32 v12, v16, v17
	v_cvt_f32_f16_e32 v16, v13
	v_cvt_f32_f16_sdwa v17, v13 dst_sel:DWORD dst_unused:UNUSED_PAD src0_sel:WORD_1
	v_cvt_f32_f16_sdwa v3, v12 dst_sel:DWORD dst_unused:UNUSED_PAD src0_sel:WORD_1
	v_pk_add_f32 v[16:17], v[18:19], v[16:17]
	s_nop 0
	v_cvt_pk_f16_f32 v13, v16, v17
	v_cvt_f32_f16_e32 v16, v14
	v_cvt_f32_f16_sdwa v17, v14 dst_sel:DWORD dst_unused:UNUSED_PAD src0_sel:WORD_1
	v_mul_f32_e32 v3, v3, v3
	v_fma_mix_f32 v3, v12, v12, v3 op_sel_hi:[1,1,0]
	s_waitcnt lgkmcnt(0)
	v_pk_add_f32 v[16:17], v[20:21], v[16:17]
	s_nop 0
	v_cvt_pk_f16_f32 v14, v16, v17
	v_cvt_f32_f16_e32 v16, v15
	v_cvt_f32_f16_sdwa v17, v15 dst_sel:DWORD dst_unused:UNUSED_PAD src0_sel:WORD_1
	v_fma_mix_f32 v3, v13, v13, v3 op_sel_hi:[1,1,0]
	v_pk_add_f32 v[16:17], v[22:23], v[16:17]
	v_fma_mix_f32 v3, v13, v13, v3 op_sel:[1,1,0] op_sel_hi:[1,1,0]
	v_cvt_pk_f16_f32 v15, v16, v17
	v_fma_mix_f32 v3, v14, v14, v3 op_sel_hi:[1,1,0]
	global_store_dwordx4 v[24:25], v[12:15], off
	v_fma_mix_f32 v3, v14, v14, v3 op_sel:[1,1,0] op_sel_hi:[1,1,0]
	s_nop 0
	v_fma_mix_f32 v3, v15, v15, v3 op_sel_hi:[1,1,0]
	s_nop 0
	v_fma_mix_f32 v3, v15, v15, v3 op_sel:[1,1,0] op_sel_hi:[1,1,0]
	s_nop 1
	v_add_f32_dpp v3, v3, v3 quad_perm:[1,0,3,2] row_mask:0xf bank_mask:0xf
	s_waitcnt lgkmcnt(0)
	s_nop 1
	v_add_f32_dpp v3, v3, v3 quad_perm:[2,3,0,1] row_mask:0xf bank_mask:0xf
	s_waitcnt lgkmcnt(0)
	s_nop 1
	v_add_f32_dpp v3, v3, v3 row_half_mirror row_mask:0xf bank_mask:0xf
	s_waitcnt lgkmcnt(0)
	s_nop 1
	v_mov_b32_dpp v11, v3 row_mirror row_mask:0xf bank_mask:0xf
	s_and_saveexec_b64 s[42:43], vcc
	s_cbranch_execz .LBB0_47
	v_lshlrev_b64 v[4:5], 6, v[4:5]
	s_waitcnt lgkmcnt(0)
	v_add_f32_e32 v34, v3, v11
	v_lshl_add_u64 v[4:5], s[36:37], 0, v[4:5]
	global_store_dwordx2 v[4:5], v[34:35], off
; DI float hlo(unsigned u) { return h2f((bf16_t)(u & 0xffffu)); }
; DI float hhi(unsigned u) { return h2f((bf16_t)(u >> 16)); }
; DI void ph_res(KP p, const bf16_t* A, int K, const bf16_t* Wt, const float* xin, char* smem, bool dry) {
;     ...
;         for (int i = 0; i < 8; ++i) {
;             const int row = (tt >> 4) + 16 * i;
;             const float4 lo = *(const float4*)(stg + row * 132 + c8 * 8), hi = *(const float4*)(stg + row * 132 + c8 * 8 + 4);
;             uint4* gp = (uint4*)(xb + (size_t)row * DM + c8 * 8);
;             const uint4 xv = *gp;
;             uint4 nv;
;             nv.x = pack2h(hlo(xv.x) + lo.x, hhi(xv.x) + lo.y); nv.y = pack2h(hlo(xv.y) + lo.z, hhi(xv.y) + lo.w);
;             nv.z = pack2h(hlo(xv.z) + hi.x, hhi(xv.z) + hi.y); nv.w = pack2h(hlo(xv.w) + hi.z, hhi(xv.w) + hi.w);
;             *gp = nv;
;             float s0 = hlo(nv.x), s1 = hhi(nv.x), s2 = hlo(nv.y), s3 = hhi(nv.y), s4 = hlo(nv.z), s5 = hhi(nv.z), s6 = hlo(nv.w), s7 = hhi(nv.w);
;             float sq = s0 * s0 + s1 * s1 + s2 * s2 + s3 * s3 + s4 * s4 + s5 * s5 + s6 * s6 + s7 * s7;
;             sq += __shfl_xor(sq, 1); sq += __shfl_xor(sq, 2); sq += __shfl_xor(sq, 4); sq += __shfl_xor(sq, 8);
;             if (c8 == 0) { float2 pv; pv.x = sq; pv.y = 0.f; *(float2*)(part + (size_t)row * 16) = pv; }
.LBB0_47:
	s_or_b64 exec, exec, s[42:43]
	v_add_u32_e32 v4, 0x50, v2
	v_ashrrev_i32_e32 v5, 31, v4
	v_lshlrev_b64 v[12:13], 11, v[4:5]
	v_lshl_add_u64 v[24:25], v[0:1], 0, v[12:13]
	v_mov_b64_e32 v[12:13], v[56:57]
	v_mov_b64_e32 v[14:15], v[58:59]
	ds_read_b128 v[16:19], v10 offset:42240
	ds_read_b128 v[20:23], v10 offset:42256
	v_cvt_f32_f16_e32 v26, v12
	v_cvt_f32_f16_sdwa v27, v12 dst_sel:DWORD dst_unused:UNUSED_PAD src0_sel:WORD_1
	s_waitcnt lgkmcnt(1)
	v_pk_add_f32 v[16:17], v[16:17], v[26:27]
	s_nop 0
	v_cvt_pk_f16_f32 v12, v16, v17
	v_cvt_f32_f16_e32 v16, v13
	v_cvt_f32_f16_sdwa v17, v13 dst_sel:DWORD dst_unused:UNUSED_PAD src0_sel:WORD_1
	v_cvt_f32_f16_sdwa v3, v12 dst_sel:DWORD dst_unused:UNUSED_PAD src0_sel:WORD_1
	v_pk_add_f32 v[16:17], v[18:19], v[16:17]
	s_nop 0
	v_cvt_pk_f16_f32 v13, v16, v17
	v_cvt_f32_f16_e32 v16, v14
	v_cvt_f32_f16_sdwa v17, v14 dst_sel:DWORD dst_unused:UNUSED_PAD src0_sel:WORD_1
	v_mul_f32_e32 v3, v3, v3
	v_fma_mix_f32 v3, v12, v12, v3 op_sel_hi:[1,1,0]
	s_waitcnt lgkmcnt(0)
	v_pk_add_f32 v[16:17], v[20:21], v[16:17]
	s_nop 0
	v_cvt_pk_f16_f32 v14, v16, v17
	v_cvt_f32_f16_e32 v16, v15
	v_cvt_f32_f16_sdwa v17, v15 dst_sel:DWORD dst_unused:UNUSED_PAD src0_sel:WORD_1
	v_fma_mix_f32 v3, v13, v13, v3 op_sel_hi:[1,1,0]
	v_pk_add_f32 v[16:17], v[22:23], v[16:17]
	v_fma_mix_f32 v3, v13, v13, v3 op_sel:[1,1,0] op_sel_hi:[1,1,0]
	v_cvt_pk_f16_f32 v15, v16, v17
	v_fma_mix_f32 v3, v14, v14, v3 op_sel_hi:[1,1,0]
	global_store_dwordx4 v[24:25], v[12:15], off
	v_fma_mix_f32 v3, v14, v14, v3 op_sel:[1,1,0] op_sel_hi:[1,1,0]
	s_nop 0
	v_fma_mix_f32 v3, v15, v15, v3 op_sel_hi:[1,1,0]
	s_nop 0
	v_fma_mix_f32 v3, v15, v15, v3 op_sel:[1,1,0] op_sel_hi:[1,1,0]
	s_nop 1
	v_add_f32_dpp v3, v3, v3 quad_perm:[1,0,3,2] row_mask:0xf bank_mask:0xf
	s_waitcnt lgkmcnt(0)
	s_nop 1
	v_add_f32_dpp v3, v3, v3 quad_perm:[2,3,0,1] row_mask:0xf bank_mask:0xf
	s_waitcnt lgkmcnt(0)
	s_nop 1
	v_add_f32_dpp v3, v3, v3 row_half_mirror row_mask:0xf bank_mask:0xf
	s_waitcnt lgkmcnt(0)
	s_nop 1
	v_mov_b32_dpp v11, v3 row_mirror row_mask:0xf bank_mask:0xf
	s_and_saveexec_b64 s[42:43], vcc
	s_cbranch_execz .LBB0_49
	v_lshlrev_b64 v[4:5], 6, v[4:5]
	s_waitcnt lgkmcnt(0)
	v_add_f32_e32 v34, v3, v11
	v_lshl_add_u64 v[4:5], s[36:37], 0, v[4:5]
	global_store_dwordx2 v[4:5], v[34:35], off
.LBB0_49:
	s_or_b64 exec, exec, s[42:43]
	v_add_u32_e32 v4, 0x60, v2
	v_ashrrev_i32_e32 v5, 31, v4
	v_lshlrev_b64 v[12:13], 11, v[4:5]
	v_lshl_add_u64 v[24:25], v[0:1], 0, v[12:13]
	v_mov_b64_e32 v[12:13], v[60:61]
	v_mov_b64_e32 v[14:15], v[62:63]
	ds_read_b128 v[16:19], v10 offset:50688
	ds_read_b128 v[20:23], v10 offset:50704
	v_cvt_f32_f16_e32 v26, v12
	v_cvt_f32_f16_sdwa v27, v12 dst_sel:DWORD dst_unused:UNUSED_PAD src0_sel:WORD_1
	s_waitcnt lgkmcnt(1)
	v_pk_add_f32 v[16:17], v[16:17], v[26:27]
	s_nop 0
	v_cvt_pk_f16_f32 v12, v16, v17
	v_cvt_f32_f16_e32 v16, v13
	v_cvt_f32_f16_sdwa v17, v13 dst_sel:DWORD dst_unused:UNUSED_PAD src0_sel:WORD_1
	v_cvt_f32_f16_sdwa v3, v12 dst_sel:DWORD dst_unused:UNUSED_PAD src0_sel:WORD_1
	v_pk_add_f32 v[16:17], v[18:19], v[16:17]
	s_nop 0
	v_cvt_pk_f16_f32 v13, v16, v17
	v_cvt_f32_f16_e32 v16, v14
	v_cvt_f32_f16_sdwa v17, v14 dst_sel:DWORD dst_unused:UNUSED_PAD src0_sel:WORD_1
	v_mul_f32_e32 v3, v3, v3
	v_fma_mix_f32 v3, v12, v12, v3 op_sel_hi:[1,1,0]
	s_waitcnt lgkmcnt(0)
	v_pk_add_f32 v[16:17], v[20:21], v[16:17]
	s_nop 0
	v_cvt_pk_f16_f32 v14, v16, v17
	v_cvt_f32_f16_e32 v16, v15
	v_cvt_f32_f16_sdwa v17, v15 dst_sel:DWORD dst_unused:UNUSED_PAD src0_sel:WORD_1
	v_fma_mix_f32 v3, v13, v13, v3 op_sel_hi:[1,1,0]
	v_pk_add_f32 v[16:17], v[22:23], v[16:17]
	v_fma_mix_f32 v3, v13, v13, v3 op_sel:[1,1,0] op_sel_hi:[1,1,0]
	v_cvt_pk_f16_f32 v15, v16, v17
	v_fma_mix_f32 v3, v14, v14, v3 op_sel_hi:[1,1,0]
	global_store_dwordx4 v[24:25], v[12:15], off
	v_fma_mix_f32 v3, v14, v14, v3 op_sel:[1,1,0] op_sel_hi:[1,1,0]
	s_nop 0
	v_fma_mix_f32 v3, v15, v15, v3 op_sel_hi:[1,1,0]
	s_nop 0
	v_fma_mix_f32 v3, v15, v15, v3 op_sel:[1,1,0] op_sel_hi:[1,1,0]
	s_nop 1
	v_add_f32_dpp v3, v3, v3 quad_perm:[1,0,3,2] row_mask:0xf bank_mask:0xf
	s_waitcnt lgkmcnt(0)
	s_nop 1
	v_add_f32_dpp v3, v3, v3 quad_perm:[2,3,0,1] row_mask:0xf bank_mask:0xf
	s_waitcnt lgkmcnt(0)
	s_nop 1
	v_add_f32_dpp v3, v3, v3 row_half_mirror row_mask:0xf bank_mask:0xf
	s_waitcnt lgkmcnt(0)
	s_nop 1
	v_mov_b32_dpp v11, v3 row_mirror row_mask:0xf bank_mask:0xf
	s_and_saveexec_b64 s[42:43], vcc
	s_cbranch_execz .LBB0_51
	v_lshlrev_b64 v[4:5], 6, v[4:5]
	s_waitcnt lgkmcnt(0)
	v_add_f32_e32 v34, v3, v11
	v_lshl_add_u64 v[4:5], s[36:37], 0, v[4:5]
	global_store_dwordx2 v[4:5], v[34:35], off
.LBB0_51:
	s_or_b64 exec, exec, s[42:43]
	v_add_u32_e32 v2, 0x70, v2
	v_ashrrev_i32_e32 v3, 31, v2
	v_lshlrev_b64 v[4:5], 11, v[2:3]
	v_lshl_add_u64 v[0:1], v[0:1], 0, v[4:5]
	v_mov_b64_e32 v[12:13], v[64:65]
	v_mov_b64_e32 v[14:15], v[66:67]
	ds_read_b128 v[16:19], v10 offset:59136
	ds_read_b128 v[20:23], v10 offset:59152
	v_cvt_f32_f16_e32 v4, v12
	v_cvt_f32_f16_sdwa v5, v12 dst_sel:DWORD dst_unused:UNUSED_PAD src0_sel:WORD_1
	s_waitcnt lgkmcnt(1)
	v_pk_add_f32 v[4:5], v[16:17], v[4:5]
	s_nop 0
	v_cvt_pk_f16_f32 v10, v4, v5
	v_cvt_f32_f16_e32 v4, v13
	v_cvt_f32_f16_sdwa v5, v13 dst_sel:DWORD dst_unused:UNUSED_PAD src0_sel:WORD_1
	v_pk_add_f32 v[4:5], v[18:19], v[4:5]
	s_nop 0
	v_cvt_pk_f16_f32 v11, v4, v5
	v_cvt_f32_f16_e32 v4, v14
	v_cvt_f32_f16_sdwa v5, v14 dst_sel:DWORD dst_unused:UNUSED_PAD src0_sel:WORD_1
	s_waitcnt lgkmcnt(0)
	v_pk_add_f32 v[4:5], v[20:21], v[4:5]
	s_nop 0
	v_cvt_pk_f16_f32 v12, v4, v5
	v_cvt_f32_f16_e32 v4, v15
	v_cvt_f32_f16_sdwa v5, v15 dst_sel:DWORD dst_unused:UNUSED_PAD src0_sel:WORD_1
	v_pk_add_f32 v[4:5], v[22:23], v[4:5]
	s_nop 0
	v_cvt_pk_f16_f32 v13, v4, v5
	global_store_dwordx4 v[0:1], v[10:13], off
	v_cvt_f32_f16_sdwa v0, v10 dst_sel:DWORD dst_unused:UNUSED_PAD src0_sel:WORD_1
	v_mul_f32_e32 v0, v0, v0
	v_fma_mix_f32 v0, v10, v10, v0 op_sel_hi:[1,1,0]
	s_nop 0
	v_fma_mix_f32 v0, v11, v11, v0 op_sel_hi:[1,1,0]
	s_nop 0
	v_fma_mix_f32 v0, v11, v11, v0 op_sel:[1,1,0] op_sel_hi:[1,1,0]
	s_nop 0
	v_fma_mix_f32 v0, v12, v12, v0 op_sel_hi:[1,1,0]
	s_nop 0
	v_fma_mix_f32 v0, v12, v12, v0 op_sel:[1,1,0] op_sel_hi:[1,1,0]
	s_nop 0
	v_fma_mix_f32 v0, v13, v13, v0 op_sel_hi:[1,1,0]
	s_nop 0
	v_fma_mix_f32 v0, v13, v13, v0 op_sel:[1,1,0] op_sel_hi:[1,1,0]
	s_nop 1
	v_add_f32_dpp v0, v0, v0 quad_perm:[1,0,3,2] row_mask:0xf bank_mask:0xf
	s_waitcnt lgkmcnt(0)
	s_nop 1
	v_add_f32_dpp v0, v0, v0 quad_perm:[2,3,0,1] row_mask:0xf bank_mask:0xf
	s_waitcnt lgkmcnt(0)
	s_nop 1
	v_add_f32_dpp v0, v0, v0 row_half_mirror row_mask:0xf bank_mask:0xf
	s_waitcnt lgkmcnt(0)
	s_nop 1
	v_mov_b32_dpp v1, v0 row_mirror row_mask:0xf bank_mask:0xf
	s_and_saveexec_b64 s[42:43], vcc
	s_cbranch_execz .LBB0_30
	s_waitcnt lgkmcnt(0)
	v_add_f32_e32 v34, v0, v1
	v_lshlrev_b64 v[0:1], 6, v[2:3]
	v_lshl_add_u64 v[0:1], s[36:37], 0, v[0:1]
	global_store_dwordx2 v[0:1], v[34:35], off
	s_branch .LBB0_30

; DI float hlo(unsigned u) { return h2f((bf16_t)(u & 0xffffu)); }
; DI float hhi(unsigned u) { return h2f((bf16_t)(u >> 16)); }
; DI int crow(int r, int h) { return (r & 3) + 8 * (r >> 2) + 4 * h; }
; DI void ph_res(KP p, const bf16_t* A, int K, const bf16_t* Wt, const float* xin, char* smem, bool dry) {
;     ...
; #pragma unroll
;         for (int i = 0; i < 2; ++i)
; #pragma unroll
;             for (int j = 0; j < 2; ++j)
; #pragma unroll
;                 for (int r = 0; r < 16; ++r) stg[(wm * 64 + i * 32 + crow(r, h)) * 132 + wn * 64 + j * 32 + l32] = acc[i][j][r];
;         __syncthreads();
;         bf16_t* xb = (bf16_t*)(p->ws + OFF_XB) + (size_t)(rt * 128) * DM + ct * 128;
;         float* part = (float*)(p->ws + OFF_RSC) + (size_t)(rt * 128) * 16 + ct * 2;
;         const int c8 = tt & 15;
; #pragma unroll
;         for (int i = 0; i < 8; ++i) {
;             const int row = (tt >> 4) + 16 * i;
;             const float4 lo = *(const float4*)(stg + row * 132 + c8 * 8), hi = *(const float4*)(stg + row * 132 + c8 * 8 + 4);
;             uint4* gp = (uint4*)(xb + (size_t)row * DM + c8 * 8);
;             const uint4 xv = *gp;
;             uint4 nv;
;             nv.x = pack2h(hlo(xv.x) + lo.x, hhi(xv.x) + lo.y); nv.y = pack2h(hlo(xv.y) + lo.z, hhi(xv.y) + lo.w);
;             nv.z = pack2h(hlo(xv.z) + hi.x, hhi(xv.z) + hi.y); nv.w = pack2h(hlo(xv.w) + hi.z, hhi(xv.w) + hi.w);
;             *gp = nv;
;             float s0 = hlo(nv.x), s1 = hhi(nv.x), s2 = hlo(nv.y), s3 = hhi(nv.y), s4 = hlo(nv.z), s5 = hhi(nv.z), s6 = hlo(nv.w), s7 = hhi(nv.w);
;             float sq = s0 * s0 + s1 * s1 + s2 * s2 + s3 * s3 + s4 * s4 + s5 * s5 + s6 * s6 + s7 * s7;
;             sq += __shfl_xor(sq, 1); sq += __shfl_xor(sq, 2); sq += __shfl_xor(sq, 4); sq += __shfl_xor(sq, 8);
;             if (c8 == 0) { float2 pv; pv.x = sq; pv.y = 0.f; *(float2*)(part + (size_t)row * 16) = pv; }
.LBB0_98:
	v_mov_b32_e32 v32, v182
	s_ashr_i32 s43, s42, 31
	v_readfirstlane_b32 s12, v32
	s_lshr_b32 s13, s12, 1
	v_and_b32_e32 v33, 31, v32
	s_and_b32 s13, s13, 0xfffffc0
	v_lshrrev_b32_e32 v34, 3, v32
	v_and_or_b32 v34, v34, 4, s13
	v_and_or_b32 v33, s12, 64, v33
	v_mul_lo_u32 v34, v34, s82
	v_lshlrev_b32_e32 v33, 2, v33
	v_add3_u32 v33, 0, v34, v33
	v_add_u32_e32 v34, 0x400, v33
	ds_write2_b32 v33, v52, v36 offset1:32
	ds_write2_b32 v33, v53, v37 offset0:132 offset1:164
	ds_write2_b32 v34, v54, v38 offset0:8 offset1:40
	ds_write2_b32 v34, v55, v39 offset0:140 offset1:172
	v_add_u32_e32 v34, 0x1000, v33
	ds_write2_b32 v34, v56, v40 offset0:32 offset1:64
	ds_write2_b32 v34, v57, v41 offset0:164 offset1:196
	v_add_u32_e32 v34, 0x1400, v33
	ds_write2_b32 v34, v58, v42 offset0:40 offset1:72
	ds_write2_b32 v34, v59, v43 offset0:172 offset1:204
	v_add_u32_e32 v34, 0x2000, v33
	ds_write2_b32 v34, v60, v44 offset0:64 offset1:96
	ds_write2_b32 v34, v61, v45 offset0:196 offset1:228
	v_add_u32_e32 v34, 0x2400, v33
	ds_write2_b32 v34, v62, v46 offset0:72 offset1:104
	ds_write2_b32 v34, v63, v47 offset0:204 offset1:236
	v_add_u32_e32 v34, 0x3000, v33
	ds_write2_b32 v34, v64, v48 offset0:96 offset1:128
	v_add_u32_e32 v34, 0x3200, v33
	ds_write2_b32 v34, v65, v49 offset0:100 offset1:132
	v_add_u32_e32 v34, 0x3400, v33
	ds_write2_b32 v34, v66, v50 offset0:104 offset1:136
	v_add_u32_e32 v34, 0x3600, v33
	ds_write2_b32 v34, v67, v51 offset0:108 offset1:140
	v_add_u32_e32 v34, 0x4000, v33
	ds_write2_b32 v34, v16, v0 offset0:128 offset1:160
	v_add_u32_e32 v0, 0x4400, v33
	ds_write2_b32 v0, v17, v1 offset0:4 offset1:36
	ds_write2_b32 v0, v18, v2 offset0:136 offset1:168
	v_add_u32_e32 v0, 0x4800, v33
	ds_write2_b32 v0, v19, v3 offset0:12 offset1:44
	v_add_u32_e32 v0, 0x5000, v33
	ds_write2_b32 v0, v20, v4 offset0:160 offset1:192
	v_add_u32_e32 v0, 0x5400, v33
	ds_write2_b32 v0, v21, v5 offset0:36 offset1:68
	ds_write2_b32 v0, v22, v6 offset0:168 offset1:200
	v_add_u32_e32 v0, 0x5800, v33
	ds_write2_b32 v0, v23, v7 offset0:44 offset1:76
	v_add_u32_e32 v0, 0x6000, v33
	s_lshl_b64 s[12:13], s[42:43], 11
	ds_write2_b32 v0, v24, v8 offset0:192 offset1:224
	v_add_u32_e32 v0, 0x6400, v33
	s_add_u32 s34, s7, s12
	ds_write2_b32 v0, v25, v9 offset0:68 offset1:100
	ds_write2_b32 v0, v26, v10 offset0:200 offset1:232
	v_add_u32_e32 v0, 0x6800, v33
	s_addc_u32 s35, s8, s13
	s_lshl_b32 s12, s36, 7
	ds_write2_b32 v0, v27, v11 offset0:76 offset1:108
	v_add_u32_e32 v0, 0x7200, v33
	s_ashr_i32 s13, s12, 31
	ds_write2_b32 v0, v28, v12 offset0:96 offset1:128
	v_add_u32_e32 v0, 0x7400, v33
	s_lshl_b64 s[12:13], s[12:13], 1
	ds_write2_b32 v0, v29, v13 offset0:100 offset1:132
	v_add_u32_e32 v0, 0x7600, v33
	s_add_u32 s12, s34, s12
	v_and_b32_e32 v11, 15, v32
	v_ashrrev_i32_e32 v2, 4, v32
	ds_write2_b32 v0, v30, v14 offset0:104 offset1:136
	v_add_u32_e32 v0, 0x7800, v33
	s_addc_u32 s13, s35, s13
	v_lshlrev_b32_e32 v34, 4, v11
	v_ashrrev_i32_e32 v3, 31, v2
	ds_write2_b32 v0, v31, v15 offset0:108 offset1:140
	v_lshl_add_u64 v[0:1], s[12:13], 0, v[34:35]
	v_lshlrev_b64 v[4:5], 11, v[2:3]
	v_lshl_add_u64 v[24:25], v[0:1], 0, v[4:5]
	s_waitcnt lgkmcnt(0)
	s_barrier
	global_load_dwordx4 v[12:15], v[24:25], off
	v_add_co_u32_e32 v26, vcc, 0x8000, v24
	s_nop 1
	v_addc_co_u32_e32 v27, vcc, 0, v25, vcc
	global_load_dwordx4 v[40:43], v[26:27], off
	v_add_co_u32_e32 v26, vcc, 0x8000, v26
	s_nop 1
	v_addc_co_u32_e32 v27, vcc, 0, v27, vcc
	global_load_dwordx4 v[44:47], v[26:27], off
	v_add_co_u32_e32 v26, vcc, 0x8000, v26
	s_nop 1
	v_addc_co_u32_e32 v27, vcc, 0, v27, vcc
	global_load_dwordx4 v[48:51], v[26:27], off
	v_add_co_u32_e32 v26, vcc, 0x8000, v26
	s_nop 1
	v_addc_co_u32_e32 v27, vcc, 0, v27, vcc
	global_load_dwordx4 v[52:55], v[26:27], off
	v_add_co_u32_e32 v26, vcc, 0x8000, v26
	s_nop 1
	v_addc_co_u32_e32 v27, vcc, 0, v27, vcc
	global_load_dwordx4 v[56:59], v[26:27], off
	v_add_co_u32_e32 v26, vcc, 0x8000, v26
	s_nop 1
	v_addc_co_u32_e32 v27, vcc, 0, v27, vcc
	global_load_dwordx4 v[60:63], v[26:27], off
	v_add_co_u32_e32 v26, vcc, 0x8000, v26
	s_nop 1
	v_addc_co_u32_e32 v27, vcc, 0, v27, vcc
	global_load_dwordx4 v[64:67], v[26:27], off
	v_cmp_lt_i32_e32 vcc, v186, v187
	v_lshl_add_u32 v4, v11, 5, 0
	s_lshl_b64 s[12:13], s[42:43], 6
	v_cndmask_b32_e32 v5, v184, v186, vcc
	v_lshlrev_b32_e32 v6, 2, v5
	v_mul_lo_u32 v5, v2, s82
	v_add_u32_e32 v10, v4, v5
	ds_read_b128 v[16:19], v10
	ds_read_b128 v[20:23], v10 offset:16
	v_cmp_lt_i32_e32 vcc, v188, v187
	s_add_u32 s34, s9, s12
	s_addc_u32 s35, s10, s13
	s_lshl_b32 s12, s36, 1
	s_ashr_i32 s13, s12, 31
	s_lshl_b64 s[12:13], s[12:13], 2
	s_add_u32 s36, s34, s12
	s_addc_u32 s37, s35, s13
	s_waitcnt vmcnt(0)
	v_cvt_f32_f16_e32 v4, v12
	v_cvt_f32_f16_sdwa v5, v12 dst_sel:DWORD dst_unused:UNUSED_PAD src0_sel:WORD_1
	v_cvt_f32_f16_e32 v8, v13
	v_cvt_f32_f16_sdwa v9, v13 dst_sel:DWORD dst_unused:UNUSED_PAD src0_sel:WORD_1
	s_waitcnt lgkmcnt(1)
	v_pk_add_f32 v[4:5], v[16:17], v[4:5]
	s_nop 0
	v_cvt_pk_f16_f32 v12, v4, v5
	v_pk_add_f32 v[4:5], v[18:19], v[8:9]
	v_cvt_f32_f16_sdwa v7, v12 dst_sel:DWORD dst_unused:UNUSED_PAD src0_sel:WORD_1
	v_cvt_pk_f16_f32 v13, v4, v5
	v_cvt_f32_f16_e32 v4, v15
	v_cvt_f32_f16_sdwa v5, v15 dst_sel:DWORD dst_unused:UNUSED_PAD src0_sel:WORD_1
	v_cvt_f32_f16_e32 v8, v14
	v_cvt_f32_f16_sdwa v9, v14 dst_sel:DWORD dst_unused:UNUSED_PAD src0_sel:WORD_1
	s_waitcnt lgkmcnt(0)
	v_pk_add_f32 v[4:5], v[22:23], v[4:5]
	s_nop 0
	v_cvt_pk_f16_f32 v15, v4, v5
	v_mul_f32_e32 v4, v7, v7
	v_fma_mix_f32 v4, v12, v12, v4 op_sel_hi:[1,1,0]
	v_pk_add_f32 v[8:9], v[20:21], v[8:9]
	v_fma_mix_f32 v4, v13, v13, v4 op_sel_hi:[1,1,0]
	v_cvt_pk_f16_f32 v14, v8, v9
	v_fma_mix_f32 v4, v13, v13, v4 op_sel:[1,1,0] op_sel_hi:[1,1,0]
	v_cndmask_b32_e32 v7, v184, v188, vcc
	v_fma_mix_f32 v4, v14, v14, v4 op_sel_hi:[1,1,0]
	v_lshlrev_b32_e32 v7, 2, v7
	v_fma_mix_f32 v4, v14, v14, v4 op_sel:[1,1,0] op_sel_hi:[1,1,0]
	v_cmp_lt_i32_e32 vcc, v189, v187
	v_fma_mix_f32 v4, v15, v15, v4 op_sel_hi:[1,1,0]
	global_store_dwordx4 v[24:25], v[12:15], off
	v_fma_mix_f32 v4, v15, v15, v4 op_sel:[1,1,0] op_sel_hi:[1,1,0]
	s_nop 1
	v_add_f32_dpp v4, v4, v4 quad_perm:[1,0,3,2] row_mask:0xf bank_mask:0xf
	v_cndmask_b32_e32 v8, v184, v189, vcc
	v_lshlrev_b32_e32 v8, 2, v8
	v_cmp_lt_i32_e32 vcc, v190, v187
	s_waitcnt lgkmcnt(0)
	s_nop 1
	v_add_f32_dpp v4, v4, v4 quad_perm:[2,3,0,1] row_mask:0xf bank_mask:0xf
	v_cndmask_b32_e32 v9, v184, v190, vcc
	v_lshlrev_b32_e32 v9, 2, v9
	v_cmp_eq_u32_e32 vcc, 0, v11
	s_waitcnt lgkmcnt(0)
	s_nop 1
	v_add_f32_dpp v4, v4, v4 row_half_mirror row_mask:0xf bank_mask:0xf
	s_waitcnt lgkmcnt(0)
	s_nop 1
	v_mov_b32_dpp v5, v4 row_mirror row_mask:0xf bank_mask:0xf
	s_and_saveexec_b64 s[42:43], vcc
	s_cbranch_execz .LBB0_100
	s_waitcnt lgkmcnt(0)
	v_add_f32_e32 v34, v4, v5
	v_lshlrev_b64 v[4:5], 6, v[2:3]
	v_lshl_add_u64 v[4:5], s[36:37], 0, v[4:5]
	global_store_dwordx2 v[4:5], v[34:35], off
